# attention tile loop: dead ds_bpermute mask computation (cmp/cndmask/shift) removed
# baseline (speedup 1.0000x reference)
.LBB0_496:
	v_max3_f32 v1, v0, v128, v112
	v_max3_f32 v1, v1, v129, v113
	v_max3_f32 v1, v1, v130, v114
	v_max3_f32 v1, v1, v131, v115
	v_max3_f32 v1, v1, v132, v116
	v_max3_f32 v1, v1, v133, v117
	v_max3_f32 v1, v1, v134, v118
	v_max3_f32 v1, v1, v135, v119
	v_max3_f32 v1, v1, v136, v120
	v_max3_f32 v1, v1, v137, v121
	v_max3_f32 v1, v1, v138, v122
	v_max3_f32 v1, v1, v139, v123
	v_max3_f32 v1, v1, v140, v124
	v_max3_f32 v1, v1, v141, v125
	v_max3_f32 v1, v1, v142, v126
	v_max3_f32 v1, v1, v143, v127
	v_mov_b32_e32 v10, v1
	s_nop 1
	v_permlane32_swap_b32_e32 v10, v1
	v_max3_f32 v1, v1, v1, v10
	v_cmp_lt_f32_e32 vcc, s33, v1
	s_cbranch_vccz .LBB0_498
	v_exp_f32_e64 v10, -v1
	v_add_f32_e32 v197, v197, v1
	v_pk_add_f32 v[142:143], v[142:143], v[0:1] op_sel:[0,1] op_sel_hi:[1,1] neg_lo:[0,1] neg_hi:[0,1]
	v_pk_add_f32 v[140:141], v[140:141], v[0:1] op_sel:[0,1] op_sel_hi:[1,1] neg_lo:[0,1] neg_hi:[0,1]
	v_pk_add_f32 v[138:139], v[138:139], v[0:1] op_sel:[0,1] op_sel_hi:[1,1] neg_lo:[0,1] neg_hi:[0,1]
	v_pk_add_f32 v[136:137], v[136:137], v[0:1] op_sel:[0,1] op_sel_hi:[1,1] neg_lo:[0,1] neg_hi:[0,1]
	v_pk_add_f32 v[134:135], v[134:135], v[0:1] op_sel:[0,1] op_sel_hi:[1,1] neg_lo:[0,1] neg_hi:[0,1]
	v_pk_add_f32 v[132:133], v[132:133], v[0:1] op_sel:[0,1] op_sel_hi:[1,1] neg_lo:[0,1] neg_hi:[0,1]
	v_pk_add_f32 v[130:131], v[130:131], v[0:1] op_sel:[0,1] op_sel_hi:[1,1] neg_lo:[0,1] neg_hi:[0,1]
	v_pk_add_f32 v[128:129], v[128:129], v[0:1] op_sel:[0,1] op_sel_hi:[1,1] neg_lo:[0,1] neg_hi:[0,1]
	v_pk_mul_f32 v[78:79], v[78:79], v[10:11] op_sel_hi:[1,0]
	v_pk_mul_f32 v[76:77], v[76:77], v[10:11] op_sel_hi:[1,0]
	v_pk_mul_f32 v[74:75], v[74:75], v[10:11] op_sel_hi:[1,0]
	v_pk_mul_f32 v[72:73], v[72:73], v[10:11] op_sel_hi:[1,0]
	v_pk_mul_f32 v[70:71], v[70:71], v[10:11] op_sel_hi:[1,0]
	v_pk_mul_f32 v[68:69], v[68:69], v[10:11] op_sel_hi:[1,0]
	v_pk_mul_f32 v[66:67], v[66:67], v[10:11] op_sel_hi:[1,0]
	v_pk_mul_f32 v[64:65], v[64:65], v[10:11] op_sel_hi:[1,0]
	v_pk_mul_f32 v[62:63], v[62:63], v[10:11] op_sel_hi:[1,0]
	v_pk_mul_f32 v[60:61], v[60:61], v[10:11] op_sel_hi:[1,0]
	v_pk_mul_f32 v[58:59], v[58:59], v[10:11] op_sel_hi:[1,0]
	v_pk_mul_f32 v[56:57], v[56:57], v[10:11] op_sel_hi:[1,0]
	v_pk_mul_f32 v[54:55], v[54:55], v[10:11] op_sel_hi:[1,0]
	v_pk_mul_f32 v[52:53], v[52:53], v[10:11] op_sel_hi:[1,0]
	v_pk_mul_f32 v[50:51], v[50:51], v[10:11] op_sel_hi:[1,0]
	v_pk_mul_f32 v[48:49], v[48:49], v[10:11] op_sel_hi:[1,0]
	v_mul_f32_e32 v241, v241, v10
	v_pk_add_f32 v[126:127], v[126:127], v[0:1] op_sel:[0,1] op_sel_hi:[1,1] neg_lo:[0,1] neg_hi:[0,1]
	v_pk_add_f32 v[124:125], v[124:125], v[0:1] op_sel:[0,1] op_sel_hi:[1,1] neg_lo:[0,1] neg_hi:[0,1]
	v_pk_add_f32 v[122:123], v[122:123], v[0:1] op_sel:[0,1] op_sel_hi:[1,1] neg_lo:[0,1] neg_hi:[0,1]
	v_pk_add_f32 v[120:121], v[120:121], v[0:1] op_sel:[0,1] op_sel_hi:[1,1] neg_lo:[0,1] neg_hi:[0,1]
	v_pk_add_f32 v[118:119], v[118:119], v[0:1] op_sel:[0,1] op_sel_hi:[1,1] neg_lo:[0,1] neg_hi:[0,1]
	v_pk_add_f32 v[116:117], v[116:117], v[0:1] op_sel:[0,1] op_sel_hi:[1,1] neg_lo:[0,1] neg_hi:[0,1]
	v_pk_add_f32 v[114:115], v[114:115], v[0:1] op_sel:[0,1] op_sel_hi:[1,1] neg_lo:[0,1] neg_hi:[0,1]
	v_pk_add_f32 v[112:113], v[112:113], v[0:1] op_sel:[0,1] op_sel_hi:[1,1] neg_lo:[0,1] neg_hi:[0,1]
